# new F-phase epilogue (hand-scheduled conv+silu, DPP row shifts) + attention LDS-DMA issue moved after first QK MFMA
# speedup vs baseline: 1.0052x; 1.0052x over previous
.LBB0_923:
	s_mov_b32 s0, s25
	s_mov_b32 s1, s7
	s_mov_b32 s6, s24
	v_add_u32_e32 v51, s18, v243
	ds_read_b64_tr_b16 v[52:53], v51 offset:24576
	ds_read_b64_tr_b16 v[54:55], v51 offset:25088
	v_add_f32_e32 v60, v82, v83
	v_add_f32_e32 v60, v84, v60
	v_add_f32_e32 v60, v85, v60
	v_add_f32_e32 v60, v86, v60
	v_add_f32_e32 v64, v87, v60
	v_cvt_pk_bf16_f32 v162, v82, v83
	v_cvt_pk_bf16_f32 v163, v84, v85
	s_waitcnt lgkmcnt(9)
	v_mfma_f32_32x32x16_bf16 v[114:129], v[194:197], v[150:153], v[2:17]
	ds_read_b64_tr_b16 v[60:61], v51 offset:28672
	ds_read_b64_tr_b16 v[62:63], v51 offset:29184
	v_add_f32_e32 v64, v88, v64
	v_add_f32_e32 v64, v89, v64
	v_add_f32_e32 v64, v90, v64
	v_add_f32_e32 v64, v91, v64
	v_cvt_pk_bf16_f32 v164, v86, v87
	v_cvt_pk_bf16_f32 v165, v88, v89
	v_lshl_add_u64 v[244:245], v[58:59], 0, s[74:75]
	s_add_i32 s7, s24, s22
	s_mov_b32 s18, m0
	s_mov_b32 m0, s7
	s_nop 0
	global_load_lds_dwordx4 v[244:245], off
	s_mov_b32 m0, s18
	v_lshl_add_u64 v[244:245], v[56:57], 0, s[74:75]
	s_add_i32 s7, s25, s23
	s_mov_b32 s18, m0
	s_mov_b32 m0, s7
	s_nop 0
	global_load_lds_dwordx4 v[244:245], off
	s_mov_b32 m0, s18
	s_waitcnt lgkmcnt(10)
	v_mfma_f32_32x32x16_bf16 v[98:113], v[190:193], v[150:153], v[2:17]
	ds_read_b64_tr_b16 v[82:83], v51 offset:25600
	ds_read_b64_tr_b16 v[84:85], v51 offset:26112
	v_add_f32_e32 v64, v92, v64
	v_add_f32_e32 v64, v93, v64
	v_add_f32_e32 v64, v94, v64
	v_add_f32_e32 v64, v95, v64
	v_cvt_pk_bf16_f32 v158, v90, v91
	v_cvt_pk_bf16_f32 v159, v92, v93
	s_waitcnt lgkmcnt(11)
	v_mfma_f32_32x32x16_bf16 v[114:129], v[186:189], v[142:145], v[114:129]
	ds_read_b64_tr_b16 v[86:87], v51 offset:29696
	ds_read_b64_tr_b16 v[88:89], v51 offset:30208
	v_add_f32_e32 v64, v96, v64
	v_add_f32_e32 v64, v97, v64
	v_add_f32_e32 v64, v66, v64
	v_add_f32_e32 v64, v67, v64
	v_cvt_pk_bf16_f32 v160, v94, v95
	v_cvt_pk_bf16_f32 v161, v96, v97
	s_waitcnt lgkmcnt(12)
	v_mfma_f32_32x32x16_bf16 v[98:113], v[182:185], v[142:145], v[98:113]
	ds_read_b64_tr_b16 v[90:91], v51 offset:26624
	ds_read_b64_tr_b16 v[92:93], v51 offset:27136
	v_add_f32_e32 v64, v68, v64
	v_add_f32_e32 v64, v69, v64
	v_add_f32_e32 v64, v70, v64
	v_add_f32_e32 v94, v71, v64
	v_cvt_pk_bf16_f32 v154, v66, v67
	v_cvt_pk_bf16_f32 v155, v68, v69
	s_waitcnt lgkmcnt(13)
	v_mfma_f32_32x32x16_bf16 v[114:129], v[178:181], v[138:141], v[114:129]
	ds_read_b64_tr_b16 v[64:65], v51 offset:30720
	ds_read_b64_tr_b16 v[66:67], v51 offset:31232
	v_add_f32_e32 v68, v72, v94
	v_add_f32_e32 v68, v73, v68
	v_add_f32_e32 v68, v74, v68
	v_add_f32_e32 v94, v75, v68
	v_cvt_pk_bf16_f32 v156, v70, v71
	v_cvt_pk_bf16_f32 v157, v72, v73
	s_waitcnt lgkmcnt(14)
	v_mfma_f32_32x32x16_bf16 v[98:113], v[174:177], v[138:141], v[98:113]
	ds_read_b64_tr_b16 v[68:69], v51 offset:27648
	ds_read_b64_tr_b16 v[70:71], v51 offset:28160
	v_add_f32_e32 v72, v76, v94
	v_add_f32_e32 v72, v77, v72
	v_add_f32_e32 v72, v78, v72
	v_add_f32_e32 v94, v79, v72
	v_cvt_pk_bf16_f32 v146, v74, v75
	v_cvt_pk_bf16_f32 v147, v76, v77
	s_waitcnt lgkmcnt(14)
	v_mfma_f32_32x32x16_bf16 v[114:129], v[170:173], v[134:137], v[114:129]
	ds_read_b64_tr_b16 v[72:73], v51 offset:31744
	ds_read_b64_tr_b16 v[74:75], v51 offset:32256
	v_add_f32_e32 v51, v80, v94
	v_add_f32_e32 v51, v81, v51
	v_add_f32_e32 v51, 0, v51
	v_cvt_pk_bf16_f32 v148, v78, v79
	v_cvt_pk_bf16_f32 v149, v80, v81
	v_mfma_f32_32x32x16_bf16 v[98:113], v[166:169], v[134:137], v[98:113]
	s_waitcnt lgkmcnt(14)
	v_mfma_f32_32x32x16_bf16 v[18:33], v[162:165], v[52:55], v[18:33]
	v_exp_f32_e32 v114, v114
	v_exp_f32_e32 v115, v115
	v_exp_f32_e32 v116, v116
	v_exp_f32_e32 v117, v117
	s_waitcnt lgkmcnt(12)
	v_mfma_f32_32x32x16_bf16 v[34:49], v[162:165], v[60:63], v[34:49]
	v_exp_f32_e32 v118, v118
	v_exp_f32_e32 v119, v119
	v_exp_f32_e32 v120, v120
	v_exp_f32_e32 v121, v121
	v_add_u32_e32 v52, s0, v240
	ds_read_b128 v[60:63], v52
	ds_read_b128 v[166:169], v52 offset:512
	s_waitcnt lgkmcnt(12)
	v_mfma_f32_32x32x16_bf16 v[18:33], v[158:161], v[82:85], v[18:33]
	v_exp_f32_e32 v122, v122
	v_exp_f32_e32 v123, v123
	v_exp_f32_e32 v124, v124
	v_exp_f32_e32 v125, v125
	ds_read_b128 v[170:173], v52 offset:2048
	ds_read_b128 v[174:177], v52 offset:2560
	s_waitcnt lgkmcnt(12)
	v_mfma_f32_32x32x16_bf16 v[34:49], v[158:161], v[86:89], v[34:49]
	v_exp_f32_e32 v126, v126
	v_exp_f32_e32 v127, v127
	v_exp_f32_e32 v128, v128
	v_exp_f32_e32 v129, v129
	ds_read_b128 v[178:181], v52 offset:4096
	ds_read_b128 v[182:185], v52 offset:4608
	s_waitcnt lgkmcnt(12)
	v_mfma_f32_32x32x16_bf16 v[18:33], v[154:157], v[90:93], v[18:33]
	v_exp_f32_e32 v98, v98
	v_exp_f32_e32 v99, v99
	v_exp_f32_e32 v100, v100
	v_exp_f32_e32 v101, v101
	ds_read_b128 v[186:189], v52 offset:6144
	ds_read_b128 v[52:55], v52 offset:6656
	s_waitcnt lgkmcnt(12)
	v_mfma_f32_32x32x16_bf16 v[34:49], v[154:157], v[64:67], v[34:49]
	v_exp_f32_e32 v102, v102
	v_exp_f32_e32 v103, v103
	v_exp_f32_e32 v104, v104
	v_exp_f32_e32 v105, v105
	s_waitcnt lgkmcnt(10)
	v_mfma_f32_32x32x16_bf16 v[18:33], v[146:149], v[68:71], v[18:33]
	v_exp_f32_e32 v106, v106
	v_exp_f32_e32 v107, v107
	v_exp_f32_e32 v108, v108
	v_exp_f32_e32 v109, v109
	s_waitcnt lgkmcnt(8)
	v_mfma_f32_32x32x16_bf16 v[34:49], v[146:149], v[72:75], v[34:49]
	v_exp_f32_e32 v110, v110
	v_exp_f32_e32 v111, v111
	v_exp_f32_e32 v112, v112
	v_exp_f32_e32 v113, v113
	s_waitcnt vmcnt(2) lgkmcnt(0)
	s_barrier
	s_add_i32 s7, s25, 0x2000
	s_cmpk_lg_i32 s25, 0x4000
	s_cselect_b32 s24, s7, 0
	v_add_u32_e32 v64, s6, v243
	ds_read_b64_tr_b16 v[190:191], v64 offset:24576
	ds_read_b64_tr_b16 v[192:193], v64 offset:25088
	s_waitcnt lgkmcnt(9)
	v_mfma_f32_32x32x16_bf16 v[82:97], v[60:63], v[150:153], v[2:17]
	v_add_f32_e32 v65, v114, v115
	v_add_f32_e32 v65, v116, v65
	v_add_f32_e32 v65, v117, v65
	v_add_f32_e32 v65, v118, v65
	v_add_f32_e32 v65, v119, v65
	v_cvt_pk_bf16_f32 v162, v114, v115
	v_cvt_pk_bf16_f32 v163, v116, v117
	ds_read_b64_tr_b16 v[60:61], v64 offset:28672
	ds_read_b64_tr_b16 v[62:63], v64 offset:29184
	s_add_i32 s6, s25, s22
	s_mov_b32 s7, m0
	s_mov_b32 m0, s6
	s_nop 0
	global_load_lds_dwordx4 v[58:59], off
	s_mov_b32 m0, s7
	s_add_i32 s6, s24, s23
	s_mov_b32 s7, m0
	s_mov_b32 m0, s6
	s_nop 0
	global_load_lds_dwordx4 v[56:57], off
	s_mov_b32 m0, s7
	s_waitcnt lgkmcnt(10)
	v_mfma_f32_32x32x16_bf16 v[66:81], v[166:169], v[150:153], v[2:17]
	v_add_f32_e32 v65, v120, v65
	v_add_f32_e32 v65, v121, v65
	v_add_f32_e32 v65, v122, v65
	v_add_f32_e32 v65, v123, v65
	v_cvt_pk_bf16_f32 v164, v118, v119
	v_cvt_pk_bf16_f32 v165, v120, v121
	ds_read_b64_tr_b16 v[114:115], v64 offset:25600
	ds_read_b64_tr_b16 v[116:117], v64 offset:26112
	s_waitcnt lgkmcnt(11)
	v_mfma_f32_32x32x16_bf16 v[82:97], v[170:173], v[142:145], v[82:97]
	v_add_f32_e32 v65, v124, v65
	v_add_f32_e32 v65, v125, v65
	v_add_f32_e32 v65, v126, v65
	v_add_f32_e32 v65, v127, v65
	v_cvt_pk_bf16_f32 v158, v122, v123
	v_cvt_pk_bf16_f32 v159, v124, v125
	ds_read_b64_tr_b16 v[118:119], v64 offset:29696
	ds_read_b64_tr_b16 v[120:121], v64 offset:30208
	s_waitcnt lgkmcnt(12)
	v_mfma_f32_32x32x16_bf16 v[66:81], v[174:177], v[142:145], v[66:81]
	v_add_f32_e32 v65, v128, v65
	v_add_f32_e32 v65, v129, v65
	v_add_f32_e32 v65, v98, v65
	v_add_f32_e32 v65, v99, v65
	v_cvt_pk_bf16_f32 v160, v126, v127
	v_cvt_pk_bf16_f32 v161, v128, v129
	ds_read_b64_tr_b16 v[122:123], v64 offset:26624
	ds_read_b64_tr_b16 v[124:125], v64 offset:27136
	s_waitcnt lgkmcnt(13)
	v_mfma_f32_32x32x16_bf16 v[82:97], v[178:181], v[138:141], v[82:97]
	v_add_f32_e32 v65, v100, v65
	v_add_f32_e32 v65, v101, v65
	v_add_f32_e32 v65, v102, v65
	v_add_f32_e32 v65, v103, v65
	v_cvt_pk_bf16_f32 v154, v98, v99
	v_cvt_pk_bf16_f32 v155, v100, v101
	ds_read_b64_tr_b16 v[98:99], v64 offset:30720
	ds_read_b64_tr_b16 v[100:101], v64 offset:31232
	s_waitcnt lgkmcnt(14)
	v_mfma_f32_32x32x16_bf16 v[66:81], v[182:185], v[138:141], v[66:81]
	v_add_f32_e32 v65, v104, v65
	v_add_f32_e32 v65, v105, v65
	v_add_f32_e32 v65, v106, v65
	v_add_f32_e32 v65, v107, v65
	v_cvt_pk_bf16_f32 v156, v102, v103
	v_cvt_pk_bf16_f32 v157, v104, v105
	ds_read_b64_tr_b16 v[102:103], v64 offset:27648
	ds_read_b64_tr_b16 v[104:105], v64 offset:28160
	s_waitcnt lgkmcnt(14)
	v_mfma_f32_32x32x16_bf16 v[82:97], v[186:189], v[134:137], v[82:97]
	v_add_f32_e32 v65, v108, v65
	v_add_f32_e32 v65, v109, v65
	v_add_f32_e32 v65, v110, v65
	v_add_f32_e32 v65, v111, v65
	v_cvt_pk_bf16_f32 v146, v106, v107
	v_cvt_pk_bf16_f32 v147, v108, v109
	ds_read_b64_tr_b16 v[106:107], v64 offset:31744
	ds_read_b64_tr_b16 v[108:109], v64 offset:32256
	v_mfma_f32_32x32x16_bf16 v[66:81], v[52:55], v[134:137], v[66:81]
	v_add_f32_e32 v52, v112, v65
	v_add_f32_e32 v52, v113, v52
	v_add_f32_e32 v52, 0, v52
	v_cvt_pk_bf16_f32 v148, v110, v111
	v_cvt_pk_bf16_f32 v149, v112, v113
	s_waitcnt lgkmcnt(14)
	v_mfma_f32_32x32x16_bf16 v[18:33], v[162:165], v[190:193], v[18:33]
	v_exp_f32_e32 v82, v82
	v_exp_f32_e32 v83, v83
	v_exp_f32_e32 v84, v84
	v_exp_f32_e32 v85, v85
	s_waitcnt lgkmcnt(12)
	v_mfma_f32_32x32x16_bf16 v[34:49], v[162:165], v[60:63], v[34:49]
	v_exp_f32_e32 v86, v86
	v_exp_f32_e32 v87, v87
	v_exp_f32_e32 v88, v88
	v_exp_f32_e32 v89, v89
	v_add_u32_e32 v53, s24, v240
	ds_read_b128 v[194:197], v53
	ds_read_b128 v[190:193], v53 offset:512
	s_waitcnt lgkmcnt(12)
	v_mfma_f32_32x32x16_bf16 v[18:33], v[158:161], v[114:117], v[18:33]
	v_exp_f32_e32 v90, v90
	v_exp_f32_e32 v91, v91
	v_exp_f32_e32 v92, v92
	v_exp_f32_e32 v93, v93
	ds_read_b128 v[186:189], v53 offset:2048
	ds_read_b128 v[182:185], v53 offset:2560
	s_waitcnt lgkmcnt(12)
	v_mfma_f32_32x32x16_bf16 v[34:49], v[158:161], v[118:121], v[34:49]
	v_exp_f32_e32 v94, v94
	v_exp_f32_e32 v95, v95
	v_exp_f32_e32 v96, v96
	v_exp_f32_e32 v97, v97
	ds_read_b128 v[178:181], v53 offset:4096
	ds_read_b128 v[174:177], v53 offset:4608
	s_waitcnt lgkmcnt(12)
	v_mfma_f32_32x32x16_bf16 v[18:33], v[154:157], v[122:125], v[18:33]
	v_exp_f32_e32 v66, v66
	v_exp_f32_e32 v67, v67
	v_exp_f32_e32 v68, v68
	v_exp_f32_e32 v69, v69
	ds_read_b128 v[170:173], v53 offset:6144
	ds_read_b128 v[166:169], v53 offset:6656
	s_waitcnt lgkmcnt(12)
	v_mfma_f32_32x32x16_bf16 v[34:49], v[154:157], v[98:101], v[34:49]
	v_exp_f32_e32 v70, v70
	v_exp_f32_e32 v71, v71
	v_exp_f32_e32 v72, v72
	v_exp_f32_e32 v73, v73
	s_waitcnt lgkmcnt(10)
	v_mfma_f32_32x32x16_bf16 v[18:33], v[146:149], v[102:105], v[18:33]
	v_exp_f32_e32 v74, v74
	v_exp_f32_e32 v75, v75
	v_exp_f32_e32 v76, v76
	v_exp_f32_e32 v77, v77
	s_waitcnt lgkmcnt(8)
	v_mfma_f32_32x32x16_bf16 v[34:49], v[146:149], v[106:109], v[34:49]
	v_exp_f32_e32 v78, v78
	v_exp_f32_e32 v79, v79
	v_exp_f32_e32 v80, v80
	v_exp_f32_e32 v81, v81
	s_add_i32 s6, s24, 0x2000
	s_waitcnt vmcnt(2) lgkmcnt(0)
	s_barrier
	s_cmpk_lg_i32 s24, 0x4000
	v_add_f32_e32 v50, v50, v51
	s_mov_b32 s18, s25
	s_cselect_b32 s25, s6, 0
	s_add_i32 s7, s1, 2
	v_lshl_add_u64 v[56:57], v[56:57], 0, s[90:91]
	v_lshl_add_u64 v[58:59], v[58:59], 0, s[90:91]
	s_cmp_ge_u32 s7, s38
	v_add_f32_e32 v50, v50, v52
	s_cbranch_scc0 .LBB0_923
	s_add_i32 s80, s1, -3
	s_add_i32 s1, s80, 1
	s_cmp_ge_u32 s1, s38
	s_cbranch_scc0 .LBB0_929

.LBB0_1246:
	v_readlane_b32 s69, v254, 62
	v_readlane_b32 s50, v255, 0
	v_readlane_b32 s51, v255, 1
	s_mov_b32 s44, s0
	v_lshl_or_b32 v178, s68, 7, v198
	v_mov_b32_e32 v179, 0
	v_lshlrev_b32_e32 v180, 2, v178
	v_mov_b32_e32 v181, 0
	v_lshl_add_u64 v[182:183], v[164:165], 0, v[180:181]
	global_load_dwordx4 v[132:135], v[182:183], off
	global_load_dwordx4 v[234:237], v[182:183], off offset:16
	v_lshl_add_u64 v[184:185], v[166:167], 0, v[180:181]
	global_load_dwordx4 v[136:139], v[184:185], off
	global_load_dwordx4 v[238:241], v[184:185], off offset:16
	v_lshl_add_u64 v[186:187], v[168:169], 0, v[180:181]
	global_load_dwordx4 v[140:143], v[186:187], off
	global_load_dwordx4 v[242:245], v[186:187], off offset:16
	v_lshl_add_u64 v[188:189], v[170:171], 0, v[180:181]
	global_load_dwordx4 v[144:147], v[188:189], off
	global_load_dwordx4 v[246:249], v[188:189], off offset:16
	v_lshl_add_u64 v[190:191], v[172:173], 0, v[180:181]
	global_load_dwordx4 v[148:151], v[190:191], off
	global_load_dwordx4 v[200:203], v[190:191], off offset:16
	v_lshl_add_u64 v[208:209], v[174:175], 0, v[180:181]
	global_load_dwordx4 v[152:155], v[208:209], off
	global_load_dwordx4 v[204:207], v[208:209], off offset:16
	v_lshl_add_u32 v184, s24, 3, v195
	s_movk_i32 s2, 0x5800
	v_mov_b64_e32 v[182:183], s[22:23]
	v_mad_i64_i32 v[182:183], s[14:15], v184, s2, v[182:183]
	v_lshl_add_u64 v[182:183], v[178:179], 2, v[182:183]
	s_mov_b64 s[4:5], 0x2c00
	v_lshl_add_u64 v[184:185], v[182:183], 0, s[4:5]
	s_mov_b64 s[4:5], 0x5800
	v_lshl_add_u64 v[186:187], v[182:183], 0, s[4:5]
	s_mov_b64 s[4:5], 0x8400
	v_lshl_add_u64 v[188:189], v[182:183], 0, s[4:5]
	v_lshl_add_u32 v190, s24, 8, v194
	s_movk_i32 s2, 0x1600
	v_mov_b64_e32 v[214:215], s[20:21]
	v_mad_i64_i32 v[214:215], s[14:15], v190, s2, v[214:215]
	v_lshl_add_u64 v[214:215], v[178:179], 1, v[214:215]
	s_mov_b32 s100, 0xbfb8aa3b
	s_mov_b64 s[38:39], exec
	s_mov_b64 exec, s[10:11]
	global_store_dwordx4 v[182:183], v[64:67], off
	global_store_dwordx4 v[182:183], v[56:59], off offset:16
	global_store_dwordx4 v[184:185], v[48:51], off
	global_store_dwordx4 v[184:185], v[4:7], off offset:16
	global_store_dwordx4 v[186:187], v[60:63], off
	global_store_dwordx4 v[186:187], v[20:23], off offset:16
	global_store_dwordx4 v[188:189], v[44:47], off
	global_store_dwordx4 v[188:189], v[8:11], off offset:16
	s_mov_b64 exec, s[8:9]
	global_store_dwordx4 v[182:183], v[52:55], off
	global_store_dwordx4 v[182:183], v[36:39], off offset:16
	global_store_dwordx4 v[184:185], v[32:35], off
	global_store_dwordx4 v[184:185], v[12:15], off offset:16
	global_store_dwordx4 v[186:187], v[40:43], off
	global_store_dwordx4 v[186:187], v[28:31], off offset:16
	global_store_dwordx4 v[188:189], v[24:27], off
	global_store_dwordx4 v[188:189], v[16:19], off offset:16
	s_mov_b64 exec, s[38:39]
	s_waitcnt vmcnt(16)
	v_mul_f32_dpp v188, v24, v144 row_shr:1 row_mask:0xf bank_mask:0xf bound_ctrl:1
	v_mul_f32_dpp v189, v25, v145 row_shr:1 row_mask:0xf bank_mask:0xf bound_ctrl:1
	v_mul_f32_dpp v190, v26, v146 row_shr:1 row_mask:0xf bank_mask:0xf bound_ctrl:1
	v_mul_f32_dpp v191, v27, v147 row_shr:1 row_mask:0xf bank_mask:0xf bound_ctrl:1
	v_mul_f32_dpp v178, v16, v246 row_shr:1 row_mask:0xf bank_mask:0xf bound_ctrl:1
	v_mul_f32_dpp v179, v17, v247 row_shr:1 row_mask:0xf bank_mask:0xf bound_ctrl:1
	v_mul_f32_dpp v208, v18, v248 row_shr:1 row_mask:0xf bank_mask:0xf bound_ctrl:1
	v_mul_f32_dpp v209, v19, v249 row_shr:1 row_mask:0xf bank_mask:0xf bound_ctrl:1
	v_pk_fma_f32 v[188:189], v[48:49], v[148:149], v[188:189]
	v_pk_fma_f32 v[190:191], v[50:51], v[150:151], v[190:191]
	v_pk_fma_f32 v[178:179], v[4:5], v[200:201], v[178:179]
	v_pk_fma_f32 v[208:209], v[6:7], v[202:203], v[208:209]
	v_pk_fma_f32 v[188:189], v[44:45], v[152:153], v[188:189]
	v_pk_fma_f32 v[190:191], v[46:47], v[154:155], v[190:191]
	v_pk_fma_f32 v[178:179], v[8:9], v[204:205], v[178:179]
	v_pk_fma_f32 v[208:209], v[10:11], v[206:207], v[208:209]
	v_pk_mul_f32 v[180:181], v[188:189], s[100:101] op_sel_hi:[1,0]
	v_pk_mul_f32 v[182:183], v[190:191], s[100:101] op_sel_hi:[1,0]
	v_pk_mul_f32 v[184:185], v[178:179], s[100:101] op_sel_hi:[1,0]
	v_pk_mul_f32 v[186:187], v[208:209], s[100:101] op_sel_hi:[1,0]
	v_exp_f32_e32 v180, v180
	v_exp_f32_e32 v181, v181
	v_exp_f32_e32 v182, v182
	v_exp_f32_e32 v183, v183
	v_exp_f32_e32 v184, v184
	v_exp_f32_e32 v185, v185
	v_exp_f32_e32 v186, v186
	v_exp_f32_e32 v187, v187
	v_pk_add_f32 v[180:181], v[180:181], 1.0 op_sel_hi:[1,0]
	v_pk_add_f32 v[182:183], v[182:183], 1.0 op_sel_hi:[1,0]
	v_pk_add_f32 v[184:185], v[184:185], 1.0 op_sel_hi:[1,0]
	v_pk_add_f32 v[186:187], v[186:187], 1.0 op_sel_hi:[1,0]
	v_rcp_f32_e32 v180, v180
	v_rcp_f32_e32 v181, v181
	v_rcp_f32_e32 v182, v182
	v_rcp_f32_e32 v183, v183
	v_rcp_f32_e32 v184, v184
	v_rcp_f32_e32 v185, v185
	v_rcp_f32_e32 v186, v186
	v_rcp_f32_e32 v187, v187
	v_pk_mul_f32 v[188:189], v[188:189], v[180:181]
	v_pk_mul_f32 v[190:191], v[190:191], v[182:183]
	v_pk_mul_f32 v[178:179], v[178:179], v[184:185]
	v_pk_mul_f32 v[208:209], v[208:209], v[186:187]
	v_mul_f32_dpp v180, v40, v132 row_shr:1 row_mask:0xf bank_mask:0xf bound_ctrl:1
	v_mul_f32_dpp v181, v41, v133 row_shr:1 row_mask:0xf bank_mask:0xf bound_ctrl:1
	v_mul_f32_dpp v182, v42, v134 row_shr:1 row_mask:0xf bank_mask:0xf bound_ctrl:1
	v_mul_f32_dpp v183, v43, v135 row_shr:1 row_mask:0xf bank_mask:0xf bound_ctrl:1
	v_mul_f32_dpp v184, v28, v234 row_shr:1 row_mask:0xf bank_mask:0xf bound_ctrl:1
	v_mul_f32_dpp v185, v29, v235 row_shr:1 row_mask:0xf bank_mask:0xf bound_ctrl:1
	v_mul_f32_dpp v186, v30, v236 row_shr:1 row_mask:0xf bank_mask:0xf bound_ctrl:1
	v_mul_f32_dpp v187, v31, v237 row_shr:1 row_mask:0xf bank_mask:0xf bound_ctrl:1
	v_pk_fma_f32 v[180:181], v[64:65], v[136:137], v[180:181]
	v_pk_fma_f32 v[182:183], v[66:67], v[138:139], v[182:183]
	v_pk_fma_f32 v[184:185], v[56:57], v[238:239], v[184:185]
	v_pk_fma_f32 v[186:187], v[58:59], v[240:241], v[186:187]
	v_pk_fma_f32 v[180:181], v[60:61], v[140:141], v[180:181]
	v_pk_fma_f32 v[182:183], v[62:63], v[142:143], v[182:183]
	v_pk_fma_f32 v[184:185], v[20:21], v[242:243], v[184:185]
	v_pk_fma_f32 v[186:187], v[22:23], v[244:245], v[186:187]
	v_pk_mul_f32 v[180:181], v[180:181], v[188:189]
	v_pk_mul_f32 v[182:183], v[182:183], v[190:191]
	v_pk_mul_f32 v[184:185], v[184:185], v[178:179]
	v_pk_mul_f32 v[186:187], v[186:187], v[208:209]
	v_cvt_pk_bf16_f32 v216, v180, v181
	v_cvt_pk_bf16_f32 v217, v182, v183
	v_cvt_pk_bf16_f32 v218, v184, v185
	v_cvt_pk_bf16_f32 v219, v186, v187
	global_store_dwordx4 v[214:215], v[216:219], off
	s_mov_b32 s4, 0x9a00
	s_mov_b32 s5, 0
	v_lshl_add_u64 v[214:215], v[214:215], 0, s[4:5]
	v_pk_mul_f32 v[188:189], v[32:33], v[144:145]
	v_pk_mul_f32 v[190:191], v[34:35], v[146:147]
	v_pk_mul_f32 v[178:179], v[12:13], v[246:247]
	v_pk_mul_f32 v[208:209], v[14:15], v[248:249]
	v_pk_fma_f32 v[188:189], v[24:25], v[148:149], v[188:189]
	v_pk_fma_f32 v[190:191], v[26:27], v[150:151], v[190:191]
	v_pk_fma_f32 v[178:179], v[16:17], v[200:201], v[178:179]
	v_pk_fma_f32 v[208:209], v[18:19], v[202:203], v[208:209]
	v_fmac_f32_dpp v188, v48, v152 row_shl:1 row_mask:0xf bank_mask:0xf bound_ctrl:1
	v_fmac_f32_dpp v189, v49, v153 row_shl:1 row_mask:0xf bank_mask:0xf bound_ctrl:1
	v_fmac_f32_dpp v190, v50, v154 row_shl:1 row_mask:0xf bank_mask:0xf bound_ctrl:1
	v_fmac_f32_dpp v191, v51, v155 row_shl:1 row_mask:0xf bank_mask:0xf bound_ctrl:1
	v_fmac_f32_dpp v178, v4, v204 row_shl:1 row_mask:0xf bank_mask:0xf bound_ctrl:1
	v_fmac_f32_dpp v179, v5, v205 row_shl:1 row_mask:0xf bank_mask:0xf bound_ctrl:1
	v_fmac_f32_dpp v208, v6, v206 row_shl:1 row_mask:0xf bank_mask:0xf bound_ctrl:1
	v_fmac_f32_dpp v209, v7, v207 row_shl:1 row_mask:0xf bank_mask:0xf bound_ctrl:1
	v_pk_mul_f32 v[180:181], v[188:189], s[100:101] op_sel_hi:[1,0]
	v_pk_mul_f32 v[182:183], v[190:191], s[100:101] op_sel_hi:[1,0]
	v_pk_mul_f32 v[184:185], v[178:179], s[100:101] op_sel_hi:[1,0]
	v_pk_mul_f32 v[186:187], v[208:209], s[100:101] op_sel_hi:[1,0]
	v_exp_f32_e32 v180, v180
	v_exp_f32_e32 v181, v181
	v_exp_f32_e32 v182, v182
	v_exp_f32_e32 v183, v183
	v_exp_f32_e32 v184, v184
	v_exp_f32_e32 v185, v185
	v_exp_f32_e32 v186, v186
	v_exp_f32_e32 v187, v187
	v_pk_add_f32 v[180:181], v[180:181], 1.0 op_sel_hi:[1,0]
	v_pk_add_f32 v[182:183], v[182:183], 1.0 op_sel_hi:[1,0]
	v_pk_add_f32 v[184:185], v[184:185], 1.0 op_sel_hi:[1,0]
	v_pk_add_f32 v[186:187], v[186:187], 1.0 op_sel_hi:[1,0]
	v_rcp_f32_e32 v180, v180
	v_rcp_f32_e32 v181, v181
	v_rcp_f32_e32 v182, v182
	v_rcp_f32_e32 v183, v183
	v_rcp_f32_e32 v184, v184
	v_rcp_f32_e32 v185, v185
	v_rcp_f32_e32 v186, v186
	v_rcp_f32_e32 v187, v187
	v_pk_mul_f32 v[188:189], v[188:189], v[180:181]
	v_pk_mul_f32 v[190:191], v[190:191], v[182:183]
	v_pk_mul_f32 v[178:179], v[178:179], v[184:185]
	v_pk_mul_f32 v[208:209], v[208:209], v[186:187]
	v_pk_mul_f32 v[180:181], v[52:53], v[132:133]
	v_pk_mul_f32 v[182:183], v[54:55], v[134:135]
	v_pk_mul_f32 v[184:185], v[36:37], v[234:235]
	v_pk_mul_f32 v[186:187], v[38:39], v[236:237]
	v_pk_fma_f32 v[180:181], v[40:41], v[136:137], v[180:181]
	v_pk_fma_f32 v[182:183], v[42:43], v[138:139], v[182:183]
	v_pk_fma_f32 v[184:185], v[28:29], v[238:239], v[184:185]
	v_pk_fma_f32 v[186:187], v[30:31], v[240:241], v[186:187]
	v_fmac_f32_dpp v180, v64, v140 row_shl:1 row_mask:0xf bank_mask:0xf bound_ctrl:1
	v_fmac_f32_dpp v181, v65, v141 row_shl:1 row_mask:0xf bank_mask:0xf bound_ctrl:1
	v_fmac_f32_dpp v182, v66, v142 row_shl:1 row_mask:0xf bank_mask:0xf bound_ctrl:1
	v_fmac_f32_dpp v183, v67, v143 row_shl:1 row_mask:0xf bank_mask:0xf bound_ctrl:1
	v_fmac_f32_dpp v184, v56, v242 row_shl:1 row_mask:0xf bank_mask:0xf bound_ctrl:1
	v_fmac_f32_dpp v185, v57, v243 row_shl:1 row_mask:0xf bank_mask:0xf bound_ctrl:1
	v_fmac_f32_dpp v186, v58, v244 row_shl:1 row_mask:0xf bank_mask:0xf bound_ctrl:1
	v_fmac_f32_dpp v187, v59, v245 row_shl:1 row_mask:0xf bank_mask:0xf bound_ctrl:1
	v_pk_mul_f32 v[180:181], v[180:181], v[188:189]
	v_pk_mul_f32 v[182:183], v[182:183], v[190:191]
	v_pk_mul_f32 v[184:185], v[184:185], v[178:179]
	v_pk_mul_f32 v[186:187], v[186:187], v[208:209]
	v_cvt_pk_bf16_f32 v216, v180, v181
	v_cvt_pk_bf16_f32 v217, v182, v183
	v_cvt_pk_bf16_f32 v218, v184, v185
	v_cvt_pk_bf16_f32 v219, v186, v187
	global_store_dwordx4 v[214:215], v[216:219], off
	s_mov_b32 s4, 0xffff7c00
	s_mov_b32 s5, -1
	v_lshl_add_u64 v[214:215], v[214:215], 0, s[4:5]
	v_pk_mul_f32 v[188:189], v[48:49], v[144:145]
	v_pk_mul_f32 v[190:191], v[50:51], v[146:147]
	v_pk_mul_f32 v[178:179], v[4:5], v[246:247]
	v_pk_mul_f32 v[208:209], v[6:7], v[248:249]
	v_pk_fma_f32 v[188:189], v[44:45], v[148:149], v[188:189]
	v_pk_fma_f32 v[190:191], v[46:47], v[150:151], v[190:191]
	v_pk_fma_f32 v[178:179], v[8:9], v[200:201], v[178:179]
	v_pk_fma_f32 v[208:209], v[10:11], v[202:203], v[208:209]
	v_pk_fma_f32 v[188:189], v[120:121], v[152:153], v[188:189]
	v_pk_fma_f32 v[190:191], v[122:123], v[154:155], v[190:191]
	v_pk_fma_f32 v[178:179], v[88:89], v[204:205], v[178:179]
	v_pk_fma_f32 v[208:209], v[90:91], v[206:207], v[208:209]
	v_pk_mul_f32 v[180:181], v[188:189], s[100:101] op_sel_hi:[1,0]
	v_pk_mul_f32 v[182:183], v[190:191], s[100:101] op_sel_hi:[1,0]
	v_pk_mul_f32 v[184:185], v[178:179], s[100:101] op_sel_hi:[1,0]
	v_pk_mul_f32 v[186:187], v[208:209], s[100:101] op_sel_hi:[1,0]
	v_exp_f32_e32 v180, v180
	v_exp_f32_e32 v181, v181
	v_exp_f32_e32 v182, v182
	v_exp_f32_e32 v183, v183
	v_exp_f32_e32 v184, v184
	v_exp_f32_e32 v185, v185
	v_exp_f32_e32 v186, v186
	v_exp_f32_e32 v187, v187
	v_pk_add_f32 v[180:181], v[180:181], 1.0 op_sel_hi:[1,0]
	v_pk_add_f32 v[182:183], v[182:183], 1.0 op_sel_hi:[1,0]
	v_pk_add_f32 v[184:185], v[184:185], 1.0 op_sel_hi:[1,0]
	v_pk_add_f32 v[186:187], v[186:187], 1.0 op_sel_hi:[1,0]
	v_rcp_f32_e32 v180, v180
	v_rcp_f32_e32 v181, v181
	v_rcp_f32_e32 v182, v182
	v_rcp_f32_e32 v183, v183
	v_rcp_f32_e32 v184, v184
	v_rcp_f32_e32 v185, v185
	v_rcp_f32_e32 v186, v186
	v_rcp_f32_e32 v187, v187
	v_pk_mul_f32 v[188:189], v[188:189], v[180:181]
	v_pk_mul_f32 v[190:191], v[190:191], v[182:183]
	v_pk_mul_f32 v[178:179], v[178:179], v[184:185]
	v_pk_mul_f32 v[208:209], v[208:209], v[186:187]
	v_pk_mul_f32 v[180:181], v[64:65], v[132:133]
	v_pk_mul_f32 v[182:183], v[66:67], v[134:135]
	v_pk_mul_f32 v[184:185], v[56:57], v[234:235]
	v_pk_mul_f32 v[186:187], v[58:59], v[236:237]
	v_pk_fma_f32 v[180:181], v[60:61], v[136:137], v[180:181]
	v_pk_fma_f32 v[182:183], v[62:63], v[138:139], v[182:183]
	v_pk_fma_f32 v[184:185], v[20:21], v[238:239], v[184:185]
	v_pk_fma_f32 v[186:187], v[22:23], v[240:241], v[186:187]
	v_pk_fma_f32 v[180:181], v[128:129], v[140:141], v[180:181]
	v_pk_fma_f32 v[182:183], v[130:131], v[142:143], v[182:183]
	v_pk_fma_f32 v[184:185], v[96:97], v[242:243], v[184:185]
	v_pk_fma_f32 v[186:187], v[98:99], v[244:245], v[186:187]
	v_pk_mul_f32 v[180:181], v[180:181], v[188:189]
	v_pk_mul_f32 v[182:183], v[182:183], v[190:191]
	v_pk_mul_f32 v[184:185], v[184:185], v[178:179]
	v_pk_mul_f32 v[186:187], v[186:187], v[208:209]
	v_cvt_pk_bf16_f32 v216, v180, v181
	v_cvt_pk_bf16_f32 v217, v182, v183
	v_cvt_pk_bf16_f32 v218, v184, v185
	v_cvt_pk_bf16_f32 v219, v186, v187
	global_store_dwordx4 v[214:215], v[216:219], off
	s_mov_b32 s4, 0x1600
	s_mov_b32 s5, 0
	v_lshl_add_u64 v[214:215], v[214:215], 0, s[4:5]
	v_pk_mul_f32 v[188:189], v[44:45], v[144:145]
	v_pk_mul_f32 v[190:191], v[46:47], v[146:147]
	v_pk_mul_f32 v[178:179], v[8:9], v[246:247]
	v_pk_mul_f32 v[208:209], v[10:11], v[248:249]
	v_pk_fma_f32 v[188:189], v[120:121], v[148:149], v[188:189]
	v_pk_fma_f32 v[190:191], v[122:123], v[150:151], v[190:191]
	v_pk_fma_f32 v[178:179], v[88:89], v[200:201], v[178:179]
	v_pk_fma_f32 v[208:209], v[90:91], v[202:203], v[208:209]
	v_pk_fma_f32 v[188:189], v[112:113], v[152:153], v[188:189]
	v_pk_fma_f32 v[190:191], v[114:115], v[154:155], v[190:191]
	v_pk_fma_f32 v[178:179], v[80:81], v[204:205], v[178:179]
	v_pk_fma_f32 v[208:209], v[82:83], v[206:207], v[208:209]
	v_pk_mul_f32 v[180:181], v[188:189], s[100:101] op_sel_hi:[1,0]
	v_pk_mul_f32 v[182:183], v[190:191], s[100:101] op_sel_hi:[1,0]
	v_pk_mul_f32 v[184:185], v[178:179], s[100:101] op_sel_hi:[1,0]
	v_pk_mul_f32 v[186:187], v[208:209], s[100:101] op_sel_hi:[1,0]
	v_exp_f32_e32 v180, v180
	v_exp_f32_e32 v181, v181
	v_exp_f32_e32 v182, v182
	v_exp_f32_e32 v183, v183
	v_exp_f32_e32 v184, v184
	v_exp_f32_e32 v185, v185
	v_exp_f32_e32 v186, v186
	v_exp_f32_e32 v187, v187
	v_pk_add_f32 v[180:181], v[180:181], 1.0 op_sel_hi:[1,0]
	v_pk_add_f32 v[182:183], v[182:183], 1.0 op_sel_hi:[1,0]
	v_pk_add_f32 v[184:185], v[184:185], 1.0 op_sel_hi:[1,0]
	v_pk_add_f32 v[186:187], v[186:187], 1.0 op_sel_hi:[1,0]
	v_rcp_f32_e32 v180, v180
	v_rcp_f32_e32 v181, v181
	v_rcp_f32_e32 v182, v182
	v_rcp_f32_e32 v183, v183
	v_rcp_f32_e32 v184, v184
	v_rcp_f32_e32 v185, v185
	v_rcp_f32_e32 v186, v186
	v_rcp_f32_e32 v187, v187
	v_pk_mul_f32 v[188:189], v[188:189], v[180:181]
	v_pk_mul_f32 v[190:191], v[190:191], v[182:183]
	v_pk_mul_f32 v[178:179], v[178:179], v[184:185]
	v_pk_mul_f32 v[208:209], v[208:209], v[186:187]
	v_pk_mul_f32 v[180:181], v[60:61], v[132:133]
	v_pk_mul_f32 v[182:183], v[62:63], v[134:135]
	v_pk_mul_f32 v[184:185], v[20:21], v[234:235]
	v_pk_mul_f32 v[186:187], v[22:23], v[236:237]
	v_pk_fma_f32 v[180:181], v[128:129], v[136:137], v[180:181]
	v_pk_fma_f32 v[182:183], v[130:131], v[138:139], v[182:183]
	v_pk_fma_f32 v[184:185], v[96:97], v[238:239], v[184:185]
	v_pk_fma_f32 v[186:187], v[98:99], v[240:241], v[186:187]
	v_pk_fma_f32 v[180:181], v[124:125], v[140:141], v[180:181]
	v_pk_fma_f32 v[182:183], v[126:127], v[142:143], v[182:183]
	v_pk_fma_f32 v[184:185], v[92:93], v[242:243], v[184:185]
	v_pk_fma_f32 v[186:187], v[94:95], v[244:245], v[186:187]
	v_pk_mul_f32 v[180:181], v[180:181], v[188:189]
	v_pk_mul_f32 v[182:183], v[182:183], v[190:191]
	v_pk_mul_f32 v[184:185], v[184:185], v[178:179]
	v_pk_mul_f32 v[186:187], v[186:187], v[208:209]
	v_cvt_pk_bf16_f32 v216, v180, v181
	v_cvt_pk_bf16_f32 v217, v182, v183
	v_cvt_pk_bf16_f32 v218, v184, v185
	v_cvt_pk_bf16_f32 v219, v186, v187
	global_store_dwordx4 v[214:215], v[216:219], off
	s_mov_b32 s4, 0x1600
	s_mov_b32 s5, 0
	v_lshl_add_u64 v[214:215], v[214:215], 0, s[4:5]
	v_pk_mul_f32 v[188:189], v[120:121], v[144:145]
	v_pk_mul_f32 v[190:191], v[122:123], v[146:147]
	v_pk_mul_f32 v[178:179], v[88:89], v[246:247]
	v_pk_mul_f32 v[208:209], v[90:91], v[248:249]
	v_pk_fma_f32 v[188:189], v[112:113], v[148:149], v[188:189]
	v_pk_fma_f32 v[190:191], v[114:115], v[150:151], v[190:191]
	v_pk_fma_f32 v[178:179], v[80:81], v[200:201], v[178:179]
	v_pk_fma_f32 v[208:209], v[82:83], v[202:203], v[208:209]
	v_pk_fma_f32 v[188:189], v[104:105], v[152:153], v[188:189]
	v_pk_fma_f32 v[190:191], v[106:107], v[154:155], v[190:191]
	v_pk_fma_f32 v[178:179], v[72:73], v[204:205], v[178:179]
	v_pk_fma_f32 v[208:209], v[74:75], v[206:207], v[208:209]
	v_pk_mul_f32 v[180:181], v[188:189], s[100:101] op_sel_hi:[1,0]
	v_pk_mul_f32 v[182:183], v[190:191], s[100:101] op_sel_hi:[1,0]
	v_pk_mul_f32 v[184:185], v[178:179], s[100:101] op_sel_hi:[1,0]
	v_pk_mul_f32 v[186:187], v[208:209], s[100:101] op_sel_hi:[1,0]
	v_exp_f32_e32 v180, v180
	v_exp_f32_e32 v181, v181
	v_exp_f32_e32 v182, v182
	v_exp_f32_e32 v183, v183
	v_exp_f32_e32 v184, v184
	v_exp_f32_e32 v185, v185
	v_exp_f32_e32 v186, v186
	v_exp_f32_e32 v187, v187
	v_pk_add_f32 v[180:181], v[180:181], 1.0 op_sel_hi:[1,0]
	v_pk_add_f32 v[182:183], v[182:183], 1.0 op_sel_hi:[1,0]
	v_pk_add_f32 v[184:185], v[184:185], 1.0 op_sel_hi:[1,0]
	v_pk_add_f32 v[186:187], v[186:187], 1.0 op_sel_hi:[1,0]
	v_rcp_f32_e32 v180, v180
	v_rcp_f32_e32 v181, v181
	v_rcp_f32_e32 v182, v182
	v_rcp_f32_e32 v183, v183
	v_rcp_f32_e32 v184, v184
	v_rcp_f32_e32 v185, v185
	v_rcp_f32_e32 v186, v186
	v_rcp_f32_e32 v187, v187
	v_pk_mul_f32 v[188:189], v[188:189], v[180:181]
	v_pk_mul_f32 v[190:191], v[190:191], v[182:183]
	v_pk_mul_f32 v[178:179], v[178:179], v[184:185]
	v_pk_mul_f32 v[208:209], v[208:209], v[186:187]
	v_pk_mul_f32 v[180:181], v[128:129], v[132:133]
	v_pk_mul_f32 v[182:183], v[130:131], v[134:135]
	v_pk_mul_f32 v[184:185], v[96:97], v[234:235]
	v_pk_mul_f32 v[186:187], v[98:99], v[236:237]
	v_pk_fma_f32 v[180:181], v[124:125], v[136:137], v[180:181]
	v_pk_fma_f32 v[182:183], v[126:127], v[138:139], v[182:183]
	v_pk_fma_f32 v[184:185], v[92:93], v[238:239], v[184:185]
	v_pk_fma_f32 v[186:187], v[94:95], v[240:241], v[186:187]
	v_pk_fma_f32 v[180:181], v[116:117], v[140:141], v[180:181]
	v_pk_fma_f32 v[182:183], v[118:119], v[142:143], v[182:183]
	v_pk_fma_f32 v[184:185], v[84:85], v[242:243], v[184:185]
	v_pk_fma_f32 v[186:187], v[86:87], v[244:245], v[186:187]
	v_pk_mul_f32 v[180:181], v[180:181], v[188:189]
	v_pk_mul_f32 v[182:183], v[182:183], v[190:191]
	v_pk_mul_f32 v[184:185], v[184:185], v[178:179]
	v_pk_mul_f32 v[186:187], v[186:187], v[208:209]
	v_cvt_pk_bf16_f32 v216, v180, v181
	v_cvt_pk_bf16_f32 v217, v182, v183
	v_cvt_pk_bf16_f32 v218, v184, v185
	v_cvt_pk_bf16_f32 v219, v186, v187
	global_store_dwordx4 v[214:215], v[216:219], off
	s_mov_b32 s4, 0x1600
	s_mov_b32 s5, 0
	v_lshl_add_u64 v[214:215], v[214:215], 0, s[4:5]
	v_pk_mul_f32 v[188:189], v[112:113], v[144:145]
	v_pk_mul_f32 v[190:191], v[114:115], v[146:147]
	v_pk_mul_f32 v[178:179], v[80:81], v[246:247]
	v_pk_mul_f32 v[208:209], v[82:83], v[248:249]
	v_pk_fma_f32 v[188:189], v[104:105], v[148:149], v[188:189]
	v_pk_fma_f32 v[190:191], v[106:107], v[150:151], v[190:191]
	v_pk_fma_f32 v[178:179], v[72:73], v[200:201], v[178:179]
	v_pk_fma_f32 v[208:209], v[74:75], v[202:203], v[208:209]
	v_pk_fma_f32 v[188:189], v[100:101], v[152:153], v[188:189]
	v_pk_fma_f32 v[190:191], v[102:103], v[154:155], v[190:191]
	v_pk_fma_f32 v[178:179], v[68:69], v[204:205], v[178:179]
	v_pk_fma_f32 v[208:209], v[70:71], v[206:207], v[208:209]
	v_pk_mul_f32 v[180:181], v[188:189], s[100:101] op_sel_hi:[1,0]
	v_pk_mul_f32 v[182:183], v[190:191], s[100:101] op_sel_hi:[1,0]
	v_pk_mul_f32 v[184:185], v[178:179], s[100:101] op_sel_hi:[1,0]
	v_pk_mul_f32 v[186:187], v[208:209], s[100:101] op_sel_hi:[1,0]
	v_exp_f32_e32 v180, v180
	v_exp_f32_e32 v181, v181
	v_exp_f32_e32 v182, v182
	v_exp_f32_e32 v183, v183
	v_exp_f32_e32 v184, v184
	v_exp_f32_e32 v185, v185
	v_exp_f32_e32 v186, v186
	v_exp_f32_e32 v187, v187
	v_pk_add_f32 v[180:181], v[180:181], 1.0 op_sel_hi:[1,0]
	v_pk_add_f32 v[182:183], v[182:183], 1.0 op_sel_hi:[1,0]
	v_pk_add_f32 v[184:185], v[184:185], 1.0 op_sel_hi:[1,0]
	v_pk_add_f32 v[186:187], v[186:187], 1.0 op_sel_hi:[1,0]
	v_rcp_f32_e32 v180, v180
	v_rcp_f32_e32 v181, v181
	v_rcp_f32_e32 v182, v182
	v_rcp_f32_e32 v183, v183
	v_rcp_f32_e32 v184, v184
	v_rcp_f32_e32 v185, v185
	v_rcp_f32_e32 v186, v186
	v_rcp_f32_e32 v187, v187
	v_pk_mul_f32 v[188:189], v[188:189], v[180:181]
	v_pk_mul_f32 v[190:191], v[190:191], v[182:183]
	v_pk_mul_f32 v[178:179], v[178:179], v[184:185]
	v_pk_mul_f32 v[208:209], v[208:209], v[186:187]
	v_pk_mul_f32 v[180:181], v[124:125], v[132:133]
	v_pk_mul_f32 v[182:183], v[126:127], v[134:135]
	v_pk_mul_f32 v[184:185], v[92:93], v[234:235]
	v_pk_mul_f32 v[186:187], v[94:95], v[236:237]
	v_pk_fma_f32 v[180:181], v[116:117], v[136:137], v[180:181]
	v_pk_fma_f32 v[182:183], v[118:119], v[138:139], v[182:183]
	v_pk_fma_f32 v[184:185], v[84:85], v[238:239], v[184:185]
	v_pk_fma_f32 v[186:187], v[86:87], v[240:241], v[186:187]
	v_pk_fma_f32 v[180:181], v[108:109], v[140:141], v[180:181]
	v_pk_fma_f32 v[182:183], v[110:111], v[142:143], v[182:183]
	v_pk_fma_f32 v[184:185], v[76:77], v[242:243], v[184:185]
	v_pk_fma_f32 v[186:187], v[78:79], v[244:245], v[186:187]
	v_pk_mul_f32 v[180:181], v[180:181], v[188:189]
	v_pk_mul_f32 v[182:183], v[182:183], v[190:191]
	v_pk_mul_f32 v[184:185], v[184:185], v[178:179]
	v_pk_mul_f32 v[186:187], v[186:187], v[208:209]
	v_cvt_pk_bf16_f32 v216, v180, v181
	v_cvt_pk_bf16_f32 v217, v182, v183
	v_cvt_pk_bf16_f32 v218, v184, v185
	v_cvt_pk_bf16_f32 v219, v186, v187
	global_store_dwordx4 v[214:215], v[216:219], off
	s_mov_b32 s4, 0x1600
	s_mov_b32 s5, 0
	v_lshl_add_u64 v[214:215], v[214:215], 0, s[4:5]
	v_pk_mul_f32 v[188:189], v[104:105], v[144:145]
	v_pk_mul_f32 v[190:191], v[106:107], v[146:147]
	v_pk_mul_f32 v[178:179], v[72:73], v[246:247]
	v_pk_mul_f32 v[208:209], v[74:75], v[248:249]
	v_pk_fma_f32 v[188:189], v[100:101], v[148:149], v[188:189]
	v_pk_fma_f32 v[190:191], v[102:103], v[150:151], v[190:191]
	v_pk_fma_f32 v[178:179], v[68:69], v[200:201], v[178:179]
	v_pk_fma_f32 v[208:209], v[70:71], v[202:203], v[208:209]
	v_pk_fma_f32 v[188:189], v[32:33], v[152:153], v[188:189]
	v_pk_fma_f32 v[190:191], v[34:35], v[154:155], v[190:191]
	v_pk_fma_f32 v[178:179], v[12:13], v[204:205], v[178:179]
	v_pk_fma_f32 v[208:209], v[14:15], v[206:207], v[208:209]
	v_pk_mul_f32 v[180:181], v[188:189], s[100:101] op_sel_hi:[1,0]
	v_pk_mul_f32 v[182:183], v[190:191], s[100:101] op_sel_hi:[1,0]
	v_pk_mul_f32 v[184:185], v[178:179], s[100:101] op_sel_hi:[1,0]
	v_pk_mul_f32 v[186:187], v[208:209], s[100:101] op_sel_hi:[1,0]
	v_exp_f32_e32 v180, v180
	v_exp_f32_e32 v181, v181
	v_exp_f32_e32 v182, v182
	v_exp_f32_e32 v183, v183
	v_exp_f32_e32 v184, v184
	v_exp_f32_e32 v185, v185
	v_exp_f32_e32 v186, v186
	v_exp_f32_e32 v187, v187
	v_pk_add_f32 v[180:181], v[180:181], 1.0 op_sel_hi:[1,0]
	v_pk_add_f32 v[182:183], v[182:183], 1.0 op_sel_hi:[1,0]
	v_pk_add_f32 v[184:185], v[184:185], 1.0 op_sel_hi:[1,0]
	v_pk_add_f32 v[186:187], v[186:187], 1.0 op_sel_hi:[1,0]
	v_rcp_f32_e32 v180, v180
	v_rcp_f32_e32 v181, v181
	v_rcp_f32_e32 v182, v182
	v_rcp_f32_e32 v183, v183
	v_rcp_f32_e32 v184, v184
	v_rcp_f32_e32 v185, v185
	v_rcp_f32_e32 v186, v186
	v_rcp_f32_e32 v187, v187
	v_pk_mul_f32 v[188:189], v[188:189], v[180:181]
	v_pk_mul_f32 v[190:191], v[190:191], v[182:183]
	v_pk_mul_f32 v[178:179], v[178:179], v[184:185]
	v_pk_mul_f32 v[208:209], v[208:209], v[186:187]
	v_pk_mul_f32 v[180:181], v[116:117], v[132:133]
	v_pk_mul_f32 v[182:183], v[118:119], v[134:135]
	v_pk_mul_f32 v[184:185], v[84:85], v[234:235]
	v_pk_mul_f32 v[186:187], v[86:87], v[236:237]
	v_pk_fma_f32 v[180:181], v[108:109], v[136:137], v[180:181]
	v_pk_fma_f32 v[182:183], v[110:111], v[138:139], v[182:183]
	v_pk_fma_f32 v[184:185], v[76:77], v[238:239], v[184:185]
	v_pk_fma_f32 v[186:187], v[78:79], v[240:241], v[186:187]
	v_pk_fma_f32 v[180:181], v[52:53], v[140:141], v[180:181]
	v_pk_fma_f32 v[182:183], v[54:55], v[142:143], v[182:183]
	v_pk_fma_f32 v[184:185], v[36:37], v[242:243], v[184:185]
	v_pk_fma_f32 v[186:187], v[38:39], v[244:245], v[186:187]
	v_pk_mul_f32 v[180:181], v[180:181], v[188:189]
	v_pk_mul_f32 v[182:183], v[182:183], v[190:191]
	v_pk_mul_f32 v[184:185], v[184:185], v[178:179]
	v_pk_mul_f32 v[186:187], v[186:187], v[208:209]
	v_cvt_pk_bf16_f32 v216, v180, v181
	v_cvt_pk_bf16_f32 v217, v182, v183
	v_cvt_pk_bf16_f32 v218, v184, v185
	v_cvt_pk_bf16_f32 v219, v186, v187
	global_store_dwordx4 v[214:215], v[216:219], off
	s_mov_b32 s4, 0x1600
	s_mov_b32 s5, 0
	v_lshl_add_u64 v[214:215], v[214:215], 0, s[4:5]
	v_pk_mul_f32 v[188:189], v[100:101], v[144:145]
	v_pk_mul_f32 v[190:191], v[102:103], v[146:147]
	v_pk_mul_f32 v[178:179], v[68:69], v[246:247]
	v_pk_mul_f32 v[208:209], v[70:71], v[248:249]
	v_pk_fma_f32 v[188:189], v[32:33], v[148:149], v[188:189]
	v_pk_fma_f32 v[190:191], v[34:35], v[150:151], v[190:191]
	v_pk_fma_f32 v[178:179], v[12:13], v[200:201], v[178:179]
	v_pk_fma_f32 v[208:209], v[14:15], v[202:203], v[208:209]
	v_pk_fma_f32 v[188:189], v[24:25], v[152:153], v[188:189]
	v_pk_fma_f32 v[190:191], v[26:27], v[154:155], v[190:191]
	v_pk_fma_f32 v[178:179], v[16:17], v[204:205], v[178:179]
	v_pk_fma_f32 v[208:209], v[18:19], v[206:207], v[208:209]
	v_pk_mul_f32 v[180:181], v[188:189], s[100:101] op_sel_hi:[1,0]
	v_pk_mul_f32 v[182:183], v[190:191], s[100:101] op_sel_hi:[1,0]
	v_pk_mul_f32 v[184:185], v[178:179], s[100:101] op_sel_hi:[1,0]
	v_pk_mul_f32 v[186:187], v[208:209], s[100:101] op_sel_hi:[1,0]
	v_exp_f32_e32 v180, v180
	v_exp_f32_e32 v181, v181
	v_exp_f32_e32 v182, v182
	v_exp_f32_e32 v183, v183
	v_exp_f32_e32 v184, v184
	v_exp_f32_e32 v185, v185
	v_exp_f32_e32 v186, v186
	v_exp_f32_e32 v187, v187
	v_pk_add_f32 v[180:181], v[180:181], 1.0 op_sel_hi:[1,0]
	v_pk_add_f32 v[182:183], v[182:183], 1.0 op_sel_hi:[1,0]
	v_pk_add_f32 v[184:185], v[184:185], 1.0 op_sel_hi:[1,0]
	v_pk_add_f32 v[186:187], v[186:187], 1.0 op_sel_hi:[1,0]
	v_rcp_f32_e32 v180, v180
	v_rcp_f32_e32 v181, v181
	v_rcp_f32_e32 v182, v182
	v_rcp_f32_e32 v183, v183
	v_rcp_f32_e32 v184, v184
	v_rcp_f32_e32 v185, v185
	v_rcp_f32_e32 v186, v186
	v_rcp_f32_e32 v187, v187
	v_pk_mul_f32 v[188:189], v[188:189], v[180:181]
	v_pk_mul_f32 v[190:191], v[190:191], v[182:183]
	v_pk_mul_f32 v[178:179], v[178:179], v[184:185]
	v_pk_mul_f32 v[208:209], v[208:209], v[186:187]
	v_pk_mul_f32 v[180:181], v[108:109], v[132:133]
	v_pk_mul_f32 v[182:183], v[110:111], v[134:135]
	v_pk_mul_f32 v[184:185], v[76:77], v[234:235]
	v_pk_mul_f32 v[186:187], v[78:79], v[236:237]
	v_pk_fma_f32 v[180:181], v[52:53], v[136:137], v[180:181]
	v_pk_fma_f32 v[182:183], v[54:55], v[138:139], v[182:183]
	v_pk_fma_f32 v[184:185], v[36:37], v[238:239], v[184:185]
	v_pk_fma_f32 v[186:187], v[38:39], v[240:241], v[186:187]
	v_pk_fma_f32 v[180:181], v[40:41], v[140:141], v[180:181]
	v_pk_fma_f32 v[182:183], v[42:43], v[142:143], v[182:183]
	v_pk_fma_f32 v[184:185], v[28:29], v[242:243], v[184:185]
	v_pk_fma_f32 v[186:187], v[30:31], v[244:245], v[186:187]
	v_pk_mul_f32 v[180:181], v[180:181], v[188:189]
	v_pk_mul_f32 v[182:183], v[182:183], v[190:191]
	v_pk_mul_f32 v[184:185], v[184:185], v[178:179]
	v_pk_mul_f32 v[186:187], v[186:187], v[208:209]
	v_cvt_pk_bf16_f32 v216, v180, v181
	v_cvt_pk_bf16_f32 v217, v182, v183
	v_cvt_pk_bf16_f32 v218, v184, v185
	v_cvt_pk_bf16_f32 v219, v186, v187
	global_store_dwordx4 v[214:215], v[216:219], off
	s_andn2_b64 vcc, exec, s[12:13]
	s_mov_b64 s[12:13], -1
	s_cbranch_vccnz .LBB0_1235

	.amdhsa_kernel _Z14fwd_megakernel4Args
		.amdhsa_group_segment_fixed_size 0
		.amdhsa_private_segment_fixed_size 0
		.amdhsa_kernarg_size 432
		.amdhsa_user_sgpr_count 2
		.amdhsa_user_sgpr_dispatch_ptr 0
		.amdhsa_user_sgpr_queue_ptr 0
		.amdhsa_user_sgpr_kernarg_segment_ptr 1
		.amdhsa_user_sgpr_dispatch_id 0
		.amdhsa_user_sgpr_kernarg_preload_length 0
		.amdhsa_user_sgpr_kernarg_preload_offset 0
		.amdhsa_user_sgpr_private_segment_size 0
		.amdhsa_uses_dynamic_stack 0
		.amdhsa_enable_private_segment 0
		.amdhsa_system_sgpr_workgroup_id_x 1
		.amdhsa_system_sgpr_workgroup_id_y 0
		.amdhsa_system_sgpr_workgroup_id_z 0
		.amdhsa_system_sgpr_workgroup_info 0
		.amdhsa_system_vgpr_workitem_id 2
		.amdhsa_next_free_vgpr 256
		.amdhsa_next_free_sgpr 102
		.amdhsa_accum_offset 256
		.amdhsa_reserve_vcc 1
		.amdhsa_float_round_mode_32 0
		.amdhsa_float_round_mode_16_64 0
		.amdhsa_float_denorm_mode_32 3
		.amdhsa_float_denorm_mode_16_64 3
		.amdhsa_dx10_clamp 1
		.amdhsa_ieee_mode 1
		.amdhsa_fp16_overflow 0
		.amdhsa_tg_split 0
		.amdhsa_exception_fp_ieee_invalid_op 0
		.amdhsa_exception_fp_denorm_src 0
		.amdhsa_exception_fp_ieee_div_zero 0
		.amdhsa_exception_fp_ieee_overflow 0
		.amdhsa_exception_fp_ieee_underflow 0
		.amdhsa_exception_fp_ieee_inexact 0
		.amdhsa_exception_int_div_zero 0
	.end_amdhsa_kernel

amdhsa.kernels:
  - .agpr_count:     0
    .args:
      - .offset:         0
        .size:           176
        .value_kind:     by_value
      - .offset:         176
        .size:           4
        .value_kind:     hidden_block_count_x
      - .offset:         180
        .size:           4
        .value_kind:     hidden_block_count_y
      - .offset:         184
        .size:           4
        .value_kind:     hidden_block_count_z
      - .offset:         188
        .size:           2
        .value_kind:     hidden_group_size_x
      - .offset:         190
        .size:           2
        .value_kind:     hidden_group_size_y
      - .offset:         192
        .size:           2
        .value_kind:     hidden_group_size_z
      - .offset:         194
        .size:           2
        .value_kind:     hidden_remainder_x
      - .offset:         196
        .size:           2
        .value_kind:     hidden_remainder_y
      - .offset:         198
        .size:           2
        .value_kind:     hidden_remainder_z
      - .offset:         216
        .size:           8
        .value_kind:     hidden_global_offset_x
      - .offset:         224
        .size:           8
        .value_kind:     hidden_global_offset_y
      - .offset:         232
        .size:           8
        .value_kind:     hidden_global_offset_z
      - .offset:         240
        .size:           2
        .value_kind:     hidden_grid_dims
      - .offset:         264
        .size:           8
        .value_kind:     hidden_multigrid_sync_arg
      - .offset:         296
        .size:           4
        .value_kind:     hidden_dynamic_lds_size
    .group_segment_fixed_size: 0
    .kernarg_segment_align: 8
    .kernarg_segment_size: 432
    .language:       OpenCL C
    .language_version:
      - 2
      - 0
    .max_flat_workgroup_size: 512
    .name:           _Z14fwd_megakernel4Args
    .private_segment_fixed_size: 0
    .sgpr_count:     108
    .sgpr_spill_count: 109
    .symbol:         _Z14fwd_megakernel4Args.kd
    .uniform_work_group_size: 1
    .uses_dynamic_stack: false
    .vgpr_count:     256
    .vgpr_spill_count: 0
    .wavefront_size: 64
